# L2 prefetch (one global_load_dword per wave per K-loop trip, 4 K-tiles ahead) in layer-0 proj GEMM only
# baseline (speedup 1.0000x reference)
.LBB0_345:
	s_xor_b64 s[34:35], s[0:1], -1
	s_cmp_lg_u32 s42, 0
	s_mov_b64 s[0:1], s[36:37]
	s_cselect_b64 s[36:37], -1, 0
	s_add_u32 s25, s38, 0x100
	v_mov_b32_e32 v2, 0
	s_addc_u32 s27, s39, 0
	s_mov_b32 s67, -2
	s_mov_b64 s[38:39], 0
	v_mov_b32_e32 v3, v2
	v_mov_b32_e32 v4, v2
	v_mov_b32_e32 v5, v2
	v_mov_b32_e32 v6, v2
	v_mov_b32_e32 v7, v2
	v_mov_b32_e32 v8, v2
	v_mov_b32_e32 v9, v2
	v_mov_b32_e32 v10, v2
	v_mov_b32_e32 v11, v2
	v_mov_b32_e32 v12, v2
	v_mov_b32_e32 v13, v2
	v_mov_b32_e32 v18, v2
	v_mov_b32_e32 v19, v2
	v_mov_b32_e32 v20, v2
	v_mov_b32_e32 v21, v2
	v_mov_b32_e32 v26, v2
	v_mov_b32_e32 v27, v2
	v_mov_b32_e32 v28, v2
	v_mov_b32_e32 v29, v2
	v_mov_b32_e32 v34, v2
	v_mov_b32_e32 v35, v2
	v_mov_b32_e32 v36, v2
	v_mov_b32_e32 v37, v2
	v_mov_b32_e32 v42, v2
	v_mov_b32_e32 v43, v2
	v_mov_b32_e32 v44, v2
	v_mov_b32_e32 v45, v2
	v_mov_b32_e32 v50, v2
	v_mov_b32_e32 v51, v2
	v_mov_b32_e32 v52, v2
	v_mov_b32_e32 v53, v2
	v_mov_b32_e32 v14, v2
	v_mov_b32_e32 v15, v2
	v_mov_b32_e32 v16, v2
	v_mov_b32_e32 v17, v2
	v_mov_b32_e32 v22, v2
	v_mov_b32_e32 v23, v2
	v_mov_b32_e32 v24, v2
	v_mov_b32_e32 v25, v2
	v_mov_b32_e32 v30, v2
	v_mov_b32_e32 v31, v2
	v_mov_b32_e32 v32, v2
	v_mov_b32_e32 v33, v2
	v_mov_b32_e32 v38, v2
	v_mov_b32_e32 v39, v2
	v_mov_b32_e32 v40, v2
	v_mov_b32_e32 v41, v2
	v_mov_b32_e32 v46, v2
	v_mov_b32_e32 v47, v2
	v_mov_b32_e32 v48, v2
	v_mov_b32_e32 v49, v2
	v_mov_b32_e32 v54, v2
	v_mov_b32_e32 v55, v2
	v_mov_b32_e32 v56, v2
	v_mov_b32_e32 v57, v2
	v_mov_b32_e32 v58, v2
	v_mov_b32_e32 v59, v2
	v_mov_b32_e32 v60, v2
	v_mov_b32_e32 v61, v2
	v_mov_b32_e32 v62, v2
	v_mov_b32_e32 v63, v2
	v_mov_b32_e32 v64, v2
	v_mov_b32_e32 v65, v2
	v_mov_b32_e32 v66, v2
	v_mov_b32_e32 v67, v2
	v_mov_b32_e32 v68, v2
	v_mov_b32_e32 v69, v2
	v_mov_b32_e32 v70, v2
	v_mov_b32_e32 v71, v2
	v_mov_b32_e32 v72, v2
	v_mov_b32_e32 v73, v2
	v_mov_b32_e32 v74, v2
	v_mov_b32_e32 v75, v2
	v_mov_b32_e32 v76, v2
	v_mov_b32_e32 v77, v2
	v_mov_b32_e32 v82, v2
	v_mov_b32_e32 v83, v2
	v_mov_b32_e32 v84, v2
	v_mov_b32_e32 v85, v2
	v_mov_b32_e32 v90, v2
	v_mov_b32_e32 v91, v2
	v_mov_b32_e32 v92, v2
	v_mov_b32_e32 v93, v2
	v_mov_b32_e32 v98, v2
	v_mov_b32_e32 v99, v2
	v_mov_b32_e32 v100, v2
	v_mov_b32_e32 v101, v2
	v_mov_b32_e32 v106, v2
	v_mov_b32_e32 v107, v2
	v_mov_b32_e32 v108, v2
	v_mov_b32_e32 v109, v2
	v_mov_b32_e32 v114, v2
	v_mov_b32_e32 v115, v2
	v_mov_b32_e32 v116, v2
	v_mov_b32_e32 v117, v2
	v_mov_b32_e32 v78, v2
	v_mov_b32_e32 v79, v2
	v_mov_b32_e32 v80, v2
	v_mov_b32_e32 v81, v2
	v_mov_b32_e32 v86, v2
	v_mov_b32_e32 v87, v2
	v_mov_b32_e32 v88, v2
	v_mov_b32_e32 v89, v2
	v_mov_b32_e32 v94, v2
	v_mov_b32_e32 v95, v2
	v_mov_b32_e32 v96, v2
	v_mov_b32_e32 v97, v2
	v_mov_b32_e32 v102, v2
	v_mov_b32_e32 v103, v2
	v_mov_b32_e32 v104, v2
	v_mov_b32_e32 v105, v2
	v_mov_b32_e32 v110, v2
	v_mov_b32_e32 v111, v2
	v_mov_b32_e32 v112, v2
	v_mov_b32_e32 v113, v2
	v_mov_b32_e32 v118, v2
	v_mov_b32_e32 v119, v2
	v_mov_b32_e32 v120, v2
	v_mov_b32_e32 v121, v2
	v_mov_b32_e32 v122, v2
	v_mov_b32_e32 v123, v2
	v_mov_b32_e32 v124, v2
	v_mov_b32_e32 v125, v2
	v_mov_b32_e32 v126, v2
	v_mov_b32_e32 v127, v2
	v_mov_b32_e32 v128, v2
	v_mov_b32_e32 v129, v2
	v_lshl_add_u64 v[146:147], s[30:31], 0, v[138:139]
	v_lshl_add_u64 v[148:149], s[30:31], 0, v[140:141]
	v_readfirstlane_b32 s98, v154
	s_add_i32 s99, s65, s66
	s_and_b32 s99, s99, 3
	s_lshl_b32 s99, s99, 6
	s_lshr_b32 s100, s98, 7
	s_lshl_b32 s100, s100, 4
	s_add_i32 s99, s99, s100
	s_lshl_b32 s99, s99, 12
	s_bitcmp1_b32 s98, 6
	s_cselect_b32 s100, s25, s30
	s_cselect_b32 s101, s27, s31
	s_cselect_b32 s98, 0x100, 0
	s_sub_i32 s99, s99, s98
	s_add_i32 s99, s99, 0x200
	s_add_u32 s100, s100, s99
	s_addc_u32 s101, s101, 0
	v_and_b32_e32 v236, 15, v154
	v_lshlrev_b32_e32 v236, 12, v236
	v_bfe_u32 v237, v154, 4, 1
	v_lshl_or_b32 v236, v237, 7, v236
	v_mov_b32_e32 v237, 0
	v_lshl_add_u64 v[234:235], s[100:101], 0, v[236:237]

.Lwe_0:
	s_waitcnt lgkmcnt(0)
	s_barrier
	s_setprio 1
	s_waitcnt lgkmcnt(0)
	v_mfma_f32_16x16x32_bf16 v[126:129], v[158:161], v[190:193], v[126:129]
	v_mfma_f32_16x16x32_bf16 v[122:125], v[166:169], v[190:193], v[122:125]
	v_mfma_f32_16x16x32_bf16 v[118:121], v[158:161], v[198:201], v[118:121]
	v_mfma_f32_16x16x32_bf16 v[110:113], v[166:169], v[198:201], v[110:113]
	global_load_dword v238, v[234:235], off
	v_lshl_add_u64 v[234:235], s[12:13], 1, v[234:235]
	v_mfma_f32_16x16x32_bf16 v[102:105], v[158:161], v[206:209], v[102:105]
	v_mfma_f32_16x16x32_bf16 v[94:97], v[166:169], v[206:209], v[94:97]
	v_mfma_f32_16x16x32_bf16 v[86:89], v[158:161], v[214:217], v[86:89]
	v_mfma_f32_16x16x32_bf16 v[78:81], v[166:169], v[214:217], v[78:81]
	v_mfma_f32_16x16x32_bf16 v[126:129], v[162:165], v[194:197], v[126:129]
	v_mfma_f32_16x16x32_bf16 v[122:125], v[170:173], v[194:197], v[122:125]
	v_mfma_f32_16x16x32_bf16 v[118:121], v[162:165], v[202:205], v[118:121]
	v_mfma_f32_16x16x32_bf16 v[110:113], v[170:173], v[202:205], v[110:113]
	v_mfma_f32_16x16x32_bf16 v[102:105], v[162:165], v[210:213], v[102:105]
	v_mfma_f32_16x16x32_bf16 v[94:97], v[170:173], v[210:213], v[94:97]
	v_mfma_f32_16x16x32_bf16 v[86:89], v[162:165], v[218:221], v[86:89]
	v_mfma_f32_16x16x32_bf16 v[78:81], v[170:173], v[218:221], v[78:81]
	s_setprio 0
	s_setprio 1
	v_mfma_f32_16x16x32_bf16 v[114:117], v[174:177], v[190:193], v[114:117]
	v_mfma_f32_16x16x32_bf16 v[106:109], v[182:185], v[190:193], v[106:109]
	v_mfma_f32_16x16x32_bf16 v[98:101], v[174:177], v[198:201], v[98:101]
	v_mfma_f32_16x16x32_bf16 v[90:93], v[182:185], v[198:201], v[90:93]
	v_mfma_f32_16x16x32_bf16 v[82:85], v[174:177], v[206:209], v[82:85]
	v_mfma_f32_16x16x32_bf16 v[74:77], v[182:185], v[206:209], v[74:77]
	v_mfma_f32_16x16x32_bf16 v[70:73], v[174:177], v[214:217], v[70:73]
	v_mfma_f32_16x16x32_bf16 v[66:69], v[182:185], v[214:217], v[66:69]
	v_mfma_f32_16x16x32_bf16 v[114:117], v[178:181], v[194:197], v[114:117]
	v_mfma_f32_16x16x32_bf16 v[106:109], v[186:189], v[194:197], v[106:109]
	v_mfma_f32_16x16x32_bf16 v[98:101], v[178:181], v[202:205], v[98:101]
	v_mfma_f32_16x16x32_bf16 v[90:93], v[186:189], v[202:205], v[90:93]
	v_mfma_f32_16x16x32_bf16 v[82:85], v[178:181], v[210:213], v[82:85]
	v_mfma_f32_16x16x32_bf16 v[74:77], v[186:189], v[210:213], v[74:77]
	v_mfma_f32_16x16x32_bf16 v[70:73], v[178:181], v[218:221], v[70:73]
	v_mfma_f32_16x16x32_bf16 v[66:69], v[186:189], v[218:221], v[66:69]
	s_setprio 0
	s_barrier
	s_add_i32 s68, s58, s46
	v_lshl_add_u64 v[222:223], s[40:41], 0, v[134:135]
	s_mov_b32 m0, s68
	ds_read_b128 v[190:193], v156 offset:16384
	ds_read_b128 v[194:197], v156 offset:17408
	ds_read_b128 v[198:201], v156 offset:18432
	ds_read_b128 v[202:205], v156 offset:19456
	ds_read_b128 v[206:209], v156 offset:20480
	ds_read_b128 v[210:213], v156 offset:21504
	ds_read_b128 v[214:217], v156 offset:22528
	ds_read_b128 v[218:221], v156 offset:23552
	global_load_lds_dwordx4 v[222:223], off
	s_add_i32 m0, s68, 0x2000
	s_add_u32 s68, s40, 0x80000
	v_lshl_add_u64 v[224:225], s[40:41], 0, v[130:131]
	s_addc_u32 s69, s41, 0
	s_add_i32 s71, s59, s46
	global_load_lds_dwordx4 v[224:225], off
	v_lshl_add_u64 v[226:227], s[68:69], 0, v[134:135]
	s_mov_b32 m0, s71
	v_lshl_add_u64 v[228:229], s[42:43], 0, v[132:133]
	global_load_lds_dwordx4 v[226:227], off
	v_lshl_add_u64 v[226:227], s[68:69], 0, v[130:131]
	s_add_i32 m0, s71, 0x2000
	s_nop 0
	global_load_lds_dwordx4 v[226:227], off
	v_lshl_add_u64 v[226:227], s[42:43], 0, v[136:137]
	s_mov_b32 m0, s49
	s_nop 0
	global_load_lds_dwordx4 v[226:227], off
	s_mov_b32 m0, s50
	s_nop 0
	global_load_lds_dwordx4 v[228:229], off
	s_cmp_eq_u32 s70, 0
	s_cbranch_scc1 .Lw8_1
	s_waitcnt vmcnt(25)
	s_branch .Lwe_1

.Lwe_1:
	s_waitcnt lgkmcnt(0)
	s_barrier
	s_setprio 1
	s_waitcnt lgkmcnt(0)
	v_mfma_f32_16x16x32_bf16 v[62:65], v[158:161], v[190:193], v[62:65]
	v_mfma_f32_16x16x32_bf16 v[58:61], v[166:169], v[190:193], v[58:61]
	v_mfma_f32_16x16x32_bf16 v[54:57], v[158:161], v[198:201], v[54:57]
	v_mfma_f32_16x16x32_bf16 v[46:49], v[166:169], v[198:201], v[46:49]
	v_mfma_f32_16x16x32_bf16 v[38:41], v[158:161], v[206:209], v[38:41]
	v_mfma_f32_16x16x32_bf16 v[30:33], v[166:169], v[206:209], v[30:33]
	v_mfma_f32_16x16x32_bf16 v[22:25], v[158:161], v[214:217], v[22:25]
	v_mfma_f32_16x16x32_bf16 v[14:17], v[166:169], v[214:217], v[14:17]
	v_mfma_f32_16x16x32_bf16 v[62:65], v[162:165], v[194:197], v[62:65]
	v_mfma_f32_16x16x32_bf16 v[58:61], v[170:173], v[194:197], v[58:61]
	v_mfma_f32_16x16x32_bf16 v[54:57], v[162:165], v[202:205], v[54:57]
	v_mfma_f32_16x16x32_bf16 v[46:49], v[170:173], v[202:205], v[46:49]
	v_mfma_f32_16x16x32_bf16 v[38:41], v[162:165], v[210:213], v[38:41]
	v_mfma_f32_16x16x32_bf16 v[30:33], v[170:173], v[210:213], v[30:33]
	v_mfma_f32_16x16x32_bf16 v[22:25], v[162:165], v[218:221], v[22:25]
	v_mfma_f32_16x16x32_bf16 v[14:17], v[170:173], v[218:221], v[14:17]
	s_setprio 0
	s_setprio 1
	v_mfma_f32_16x16x32_bf16 v[50:53], v[174:177], v[190:193], v[50:53]
	v_mfma_f32_16x16x32_bf16 v[42:45], v[182:185], v[190:193], v[42:45]
	v_mfma_f32_16x16x32_bf16 v[34:37], v[174:177], v[198:201], v[34:37]
	v_mfma_f32_16x16x32_bf16 v[26:29], v[182:185], v[198:201], v[26:29]
	v_mfma_f32_16x16x32_bf16 v[18:21], v[174:177], v[206:209], v[18:21]
	v_mfma_f32_16x16x32_bf16 v[10:13], v[182:185], v[206:209], v[10:13]
	v_mfma_f32_16x16x32_bf16 v[6:9], v[174:177], v[214:217], v[6:9]
	v_mfma_f32_16x16x32_bf16 v[2:5], v[182:185], v[214:217], v[2:5]
	v_mfma_f32_16x16x32_bf16 v[50:53], v[178:181], v[194:197], v[50:53]
	v_mfma_f32_16x16x32_bf16 v[42:45], v[186:189], v[194:197], v[42:45]
	v_mfma_f32_16x16x32_bf16 v[34:37], v[178:181], v[202:205], v[34:37]
	v_mfma_f32_16x16x32_bf16 v[26:29], v[186:189], v[202:205], v[26:29]
	v_mfma_f32_16x16x32_bf16 v[18:21], v[178:181], v[210:213], v[18:21]
	v_mfma_f32_16x16x32_bf16 v[10:13], v[186:189], v[210:213], v[10:13]
	v_mfma_f32_16x16x32_bf16 v[6:9], v[178:181], v[218:221], v[6:9]
	v_mfma_f32_16x16x32_bf16 v[2:5], v[186:189], v[218:221], v[2:5]
	s_setprio 0
	s_barrier
	s_add_i32 s68, 0, 0x18000
	v_add_u32_e32 v157, s68, v150
	s_add_i32 s69, 0, 0x1c000
	ds_read_b128 v[158:161], v157
	ds_read_b128 v[162:165], v157 offset:1024
	ds_read_b128 v[166:169], v157 offset:2048
	ds_read_b128 v[170:173], v157 offset:3072
	v_add_u32_e32 v157, s69, v150
	ds_read_b128 v[174:177], v157
	ds_read_b128 v[178:181], v157 offset:1024
	ds_read_b128 v[182:185], v157 offset:2048
	ds_read_b128 v[186:189], v157 offset:3072
	s_add_u32 s42, s42, 0x80000
	s_addc_u32 s43, s43, 0
	s_mov_b32 m0, s51
	v_lshl_add_u64 v[230:231], s[42:43], 0, v[136:137]
	ds_read_b128 v[190:193], v156 offset:32768
	ds_read_b128 v[194:197], v156 offset:33792
	ds_read_b128 v[198:201], v156 offset:34816
	ds_read_b128 v[202:205], v156 offset:35840
	ds_read_b128 v[206:209], v156 offset:36864
	ds_read_b128 v[210:213], v156 offset:37888
	ds_read_b128 v[214:217], v156 offset:38912
	ds_read_b128 v[218:221], v156 offset:39936
	global_load_lds_dwordx4 v[230:231], off
	v_lshl_add_u64 v[230:231], s[42:43], 0, v[132:133]
	s_mov_b32 m0, s52
	s_nop 0
	global_load_lds_dwordx4 v[230:231], off
	s_waitcnt vmcnt(9)
	s_waitcnt lgkmcnt(0)
	s_barrier
	s_setprio 1
	s_waitcnt lgkmcnt(0)
	v_mfma_f32_16x16x32_bf16 v[126:129], v[158:161], v[190:193], v[126:129]
	v_mfma_f32_16x16x32_bf16 v[122:125], v[166:169], v[190:193], v[122:125]
	v_mfma_f32_16x16x32_bf16 v[118:121], v[158:161], v[198:201], v[118:121]
	v_mfma_f32_16x16x32_bf16 v[110:113], v[166:169], v[198:201], v[110:113]
	v_mfma_f32_16x16x32_bf16 v[102:105], v[158:161], v[206:209], v[102:105]
	v_mfma_f32_16x16x32_bf16 v[94:97], v[166:169], v[206:209], v[94:97]
	v_mfma_f32_16x16x32_bf16 v[86:89], v[158:161], v[214:217], v[86:89]
	v_mfma_f32_16x16x32_bf16 v[78:81], v[166:169], v[214:217], v[78:81]
	v_mfma_f32_16x16x32_bf16 v[126:129], v[162:165], v[194:197], v[126:129]
	v_mfma_f32_16x16x32_bf16 v[122:125], v[170:173], v[194:197], v[122:125]
	v_mfma_f32_16x16x32_bf16 v[118:121], v[162:165], v[202:205], v[118:121]
	v_mfma_f32_16x16x32_bf16 v[110:113], v[170:173], v[202:205], v[110:113]
	v_mfma_f32_16x16x32_bf16 v[102:105], v[162:165], v[210:213], v[102:105]
	v_mfma_f32_16x16x32_bf16 v[94:97], v[170:173], v[210:213], v[94:97]
	v_mfma_f32_16x16x32_bf16 v[86:89], v[162:165], v[218:221], v[86:89]
	v_mfma_f32_16x16x32_bf16 v[78:81], v[170:173], v[218:221], v[78:81]
	s_setprio 0
	s_setprio 1
	v_mfma_f32_16x16x32_bf16 v[114:117], v[174:177], v[190:193], v[114:117]
	v_mfma_f32_16x16x32_bf16 v[106:109], v[182:185], v[190:193], v[106:109]
	v_mfma_f32_16x16x32_bf16 v[98:101], v[174:177], v[198:201], v[98:101]
	v_mfma_f32_16x16x32_bf16 v[90:93], v[182:185], v[198:201], v[90:93]
	v_mfma_f32_16x16x32_bf16 v[82:85], v[174:177], v[206:209], v[82:85]
	v_mfma_f32_16x16x32_bf16 v[74:77], v[182:185], v[206:209], v[74:77]
	v_mfma_f32_16x16x32_bf16 v[70:73], v[174:177], v[214:217], v[70:73]
	v_mfma_f32_16x16x32_bf16 v[66:69], v[182:185], v[214:217], v[66:69]
	v_mfma_f32_16x16x32_bf16 v[114:117], v[178:181], v[194:197], v[114:117]
	v_mfma_f32_16x16x32_bf16 v[106:109], v[186:189], v[194:197], v[106:109]
	v_mfma_f32_16x16x32_bf16 v[98:101], v[178:181], v[202:205], v[98:101]
	v_mfma_f32_16x16x32_bf16 v[90:93], v[186:189], v[202:205], v[90:93]
	v_mfma_f32_16x16x32_bf16 v[82:85], v[178:181], v[210:213], v[82:85]
	v_mfma_f32_16x16x32_bf16 v[74:77], v[186:189], v[210:213], v[74:77]
	v_mfma_f32_16x16x32_bf16 v[70:73], v[178:181], v[218:221], v[70:73]
	v_mfma_f32_16x16x32_bf16 v[66:69], v[186:189], v[218:221], v[66:69]
	s_setprio 0
	s_barrier
	s_add_i32 s42, s68, s46
	v_lshl_add_u64 v[222:223], v[222:223], 0, s[12:13]
	s_mov_b32 m0, s42
	ds_read_b128 v[190:193], v156 offset:49152
	ds_read_b128 v[194:197], v156 offset:50176
	ds_read_b128 v[198:201], v156 offset:51200
	ds_read_b128 v[202:205], v156 offset:52224
	ds_read_b128 v[206:209], v156 offset:53248
	ds_read_b128 v[210:213], v156 offset:54272
	ds_read_b128 v[214:217], v156 offset:55296
	ds_read_b128 v[218:221], v156 offset:56320
	global_load_lds_dwordx4 v[222:223], off
	s_add_i32 m0, s42, 0x2000
	s_add_u32 s40, s40, 0x80080
	v_lshl_add_u64 v[222:223], v[224:225], 0, s[12:13]
	s_addc_u32 s41, s41, 0
	s_add_i32 s42, s69, s46
	global_load_lds_dwordx4 v[222:223], off
	v_lshl_add_u64 v[222:223], s[40:41], 0, v[134:135]
	s_mov_b32 m0, s42
	s_nop 0
	global_load_lds_dwordx4 v[222:223], off
	v_lshl_add_u64 v[222:223], s[40:41], 0, v[130:131]
	s_add_i32 m0, s42, 0x2000
	s_nop 0
	global_load_lds_dwordx4 v[222:223], off
	v_lshl_add_u64 v[222:223], v[226:227], 0, s[12:13]
	s_mov_b32 m0, s54
	s_nop 0
	global_load_lds_dwordx4 v[222:223], off
	v_lshl_add_u64 v[222:223], v[228:229], 0, s[12:13]
	s_mov_b32 m0, s55
	s_nop 0
	global_load_lds_dwordx4 v[222:223], off
	s_waitcnt vmcnt(8)
	s_waitcnt lgkmcnt(0)
	s_barrier
	s_setprio 1
	s_waitcnt lgkmcnt(0)
	v_mfma_f32_16x16x32_bf16 v[62:65], v[158:161], v[190:193], v[62:65]
	v_mfma_f32_16x16x32_bf16 v[58:61], v[166:169], v[190:193], v[58:61]
	v_mfma_f32_16x16x32_bf16 v[54:57], v[158:161], v[198:201], v[54:57]
	v_mfma_f32_16x16x32_bf16 v[46:49], v[166:169], v[198:201], v[46:49]
	v_mfma_f32_16x16x32_bf16 v[38:41], v[158:161], v[206:209], v[38:41]
	v_mfma_f32_16x16x32_bf16 v[30:33], v[166:169], v[206:209], v[30:33]
	v_mfma_f32_16x16x32_bf16 v[22:25], v[158:161], v[214:217], v[22:25]
	v_mfma_f32_16x16x32_bf16 v[14:17], v[166:169], v[214:217], v[14:17]
	v_mfma_f32_16x16x32_bf16 v[62:65], v[162:165], v[194:197], v[62:65]
	v_mfma_f32_16x16x32_bf16 v[58:61], v[170:173], v[194:197], v[58:61]
	v_mfma_f32_16x16x32_bf16 v[54:57], v[162:165], v[202:205], v[54:57]
	v_mfma_f32_16x16x32_bf16 v[46:49], v[170:173], v[202:205], v[46:49]
	v_mfma_f32_16x16x32_bf16 v[38:41], v[162:165], v[210:213], v[38:41]
	v_mfma_f32_16x16x32_bf16 v[30:33], v[170:173], v[210:213], v[30:33]
	v_mfma_f32_16x16x32_bf16 v[22:25], v[162:165], v[218:221], v[22:25]
	v_mfma_f32_16x16x32_bf16 v[14:17], v[170:173], v[218:221], v[14:17]
	s_setprio 0
	s_setprio 1
	v_mfma_f32_16x16x32_bf16 v[50:53], v[174:177], v[190:193], v[50:53]
	v_mfma_f32_16x16x32_bf16 v[42:45], v[182:185], v[190:193], v[42:45]
	v_mfma_f32_16x16x32_bf16 v[34:37], v[174:177], v[198:201], v[34:37]
	v_mfma_f32_16x16x32_bf16 v[26:29], v[182:185], v[198:201], v[26:29]
	v_mfma_f32_16x16x32_bf16 v[18:21], v[174:177], v[206:209], v[18:21]
	v_mfma_f32_16x16x32_bf16 v[10:13], v[182:185], v[206:209], v[10:13]
	v_mfma_f32_16x16x32_bf16 v[6:9], v[174:177], v[214:217], v[6:9]
	v_mfma_f32_16x16x32_bf16 v[2:5], v[182:185], v[214:217], v[2:5]
	v_mfma_f32_16x16x32_bf16 v[50:53], v[178:181], v[194:197], v[50:53]
	v_mfma_f32_16x16x32_bf16 v[42:45], v[186:189], v[194:197], v[42:45]
	v_mfma_f32_16x16x32_bf16 v[34:37], v[178:181], v[202:205], v[34:37]
	v_mfma_f32_16x16x32_bf16 v[26:29], v[186:189], v[202:205], v[26:29]
	v_mfma_f32_16x16x32_bf16 v[18:21], v[178:181], v[210:213], v[18:21]
	v_mfma_f32_16x16x32_bf16 v[10:13], v[186:189], v[210:213], v[10:13]
	v_mfma_f32_16x16x32_bf16 v[6:9], v[178:181], v[218:221], v[6:9]
	v_mfma_f32_16x16x32_bf16 v[2:5], v[186:189], v[218:221], v[2:5]
	s_setprio 0
	s_barrier
	s_add_i32 s67, s67, 2
	s_add_u32 s38, s38, 0x100
	s_addc_u32 s39, s39, 0
	s_cmp_gt_u32 s67, 29
	s_cbranch_scc0 .LBB0_346
	s_and_b64 vcc, exec, s[14:15]
	s_cbranch_vccnz .LBB0_351
	s_mov_b64 s[30:31], -1
	s_and_b64 vcc, exec, s[34:35]
	s_cbranch_vccnz .LBB0_352

	.amdhsa_kernel _Z10fwd_kernel6Params
		.amdhsa_group_segment_fixed_size 0
		.amdhsa_private_segment_fixed_size 0
		.amdhsa_kernarg_size 520
		.amdhsa_user_sgpr_count 2
		.amdhsa_user_sgpr_dispatch_ptr 0
		.amdhsa_user_sgpr_queue_ptr 0
		.amdhsa_user_sgpr_kernarg_segment_ptr 1
		.amdhsa_user_sgpr_dispatch_id 0
		.amdhsa_user_sgpr_kernarg_preload_length 0
		.amdhsa_user_sgpr_kernarg_preload_offset 0
		.amdhsa_user_sgpr_private_segment_size 0
		.amdhsa_uses_dynamic_stack 0
		.amdhsa_enable_private_segment 0
		.amdhsa_system_sgpr_workgroup_id_x 1
		.amdhsa_system_sgpr_workgroup_id_y 0
		.amdhsa_system_sgpr_workgroup_id_z 0
		.amdhsa_system_sgpr_workgroup_info 0
		.amdhsa_system_vgpr_workitem_id 2
		.amdhsa_next_free_vgpr 239
		.amdhsa_next_free_sgpr 102
		.amdhsa_accum_offset 240
		.amdhsa_reserve_vcc 1
		.amdhsa_float_round_mode_32 0
		.amdhsa_float_round_mode_16_64 0
		.amdhsa_float_denorm_mode_32 3
		.amdhsa_float_denorm_mode_16_64 3
		.amdhsa_dx10_clamp 1
		.amdhsa_ieee_mode 1
		.amdhsa_fp16_overflow 0
		.amdhsa_tg_split 0
		.amdhsa_exception_fp_ieee_invalid_op 0
		.amdhsa_exception_fp_denorm_src 0
		.amdhsa_exception_fp_ieee_div_zero 0
		.amdhsa_exception_fp_ieee_overflow 0
		.amdhsa_exception_fp_ieee_underflow 0
		.amdhsa_exception_fp_ieee_inexact 0
		.amdhsa_exception_int_div_zero 0
	.end_amdhsa_kernel

amdhsa.kernels:
  - .agpr_count:     0
    .args:
      - .offset:         0
        .size:           264
        .value_kind:     by_value
      - .offset:         264
        .size:           4
        .value_kind:     hidden_block_count_x
      - .offset:         268
        .size:           4
        .value_kind:     hidden_block_count_y
      - .offset:         272
        .size:           4
        .value_kind:     hidden_block_count_z
      - .offset:         276
        .size:           2
        .value_kind:     hidden_group_size_x
      - .offset:         278
        .size:           2
        .value_kind:     hidden_group_size_y
      - .offset:         280
        .size:           2
        .value_kind:     hidden_group_size_z
      - .offset:         282
        .size:           2
        .value_kind:     hidden_remainder_x
      - .offset:         284
        .size:           2
        .value_kind:     hidden_remainder_y
      - .offset:         286
        .size:           2
        .value_kind:     hidden_remainder_z
      - .offset:         304
        .size:           8
        .value_kind:     hidden_global_offset_x
      - .offset:         312
        .size:           8
        .value_kind:     hidden_global_offset_y
      - .offset:         320
        .size:           8
        .value_kind:     hidden_global_offset_z
      - .offset:         328
        .size:           2
        .value_kind:     hidden_grid_dims
      - .offset:         352
        .size:           8
        .value_kind:     hidden_multigrid_sync_arg
      - .offset:         384
        .size:           4
        .value_kind:     hidden_dynamic_lds_size
    .group_segment_fixed_size: 0
    .kernarg_segment_align: 8
    .kernarg_segment_size: 520
    .language:       OpenCL C
    .language_version:
      - 2
      - 0
    .max_flat_workgroup_size: 512
    .name:           _Z10fwd_kernel6Params
    .private_segment_fixed_size: 0
    .sgpr_count:     108
    .sgpr_spill_count: 105
    .symbol:         _Z10fwd_kernel6Params.kd
    .uniform_work_group_size: 1
    .uses_dynamic_stack: false
    .vgpr_count:     239
    .vgpr_spill_count: 0
    .wavefront_size: 64
